# fill_rowscales (up, gemm1): the per-tile row-scale loop is split across the two wave halves (waves 4-7 take odd tiles), halving its serial load-latency chain
# baseline (speedup 1.0000x reference)
; __device__ __forceinline__ void fill_rowscales(float* rsl, const float* ssq, float inv_n, const g8::Order& S) {
;   const int tid = opaque_tid();
;   g8::Unit u;
;   __syncthreads();
;   for (int i = 0; S.next(i, u); ++i) {
;     if (tid < 256) {
;       const float4* s4 = (const float4*)(ssq + (size_t)(u.pm * 256 + tid) * 16);
;       float s = 0.f;
;       for (int k = 0; k < 4; ++k) { float4 v = s4[k]; s += v.x + v.y + v.z + v.w; }
;       rsl[i * 256 + tid] = rsqrtf(s * inv_n + EPS);
;     }
;   }
;   __syncthreads();
; }
; __device__ __forceinline__ void phase_gemm1(const Params& p, int l, char* lds) {
;     ...
;   fill_rowscales(rsl, (const float*)(WS(p) + O_SSQ), 1.f / DM, S);
.LBB0_181:
	s_mov_b32 s0, 0
	s_ashr_i32 s1, s0, 31
	s_add_u32 s0, s82, s0
	s_addc_u32 s1, s83, s1
	s_add_u32 s0, s0, 0x9a00000
	v_mov_b32_e32 v0, v145
	s_movk_i32 s2, 0x100
	s_addc_u32 s1, s1, 0
	s_mov_b64 s[6:7], s[70:71]
	s_mov_b64 s[4:5], -1
	v_lshl_add_u32 v2, v0, 2, v190
	v_readfirstlane_b32 s2, v0
	s_cmp_lt_u32 s2, 0x100
	s_cbranch_scc1 .Lfr_g1_lo
	s_add_u32 s6, s6, s68
	s_addc_u32 s7, s7, s62
	v_and_b32_e32 v0, 0xff, v0
.Lfr_g1_lo:
	s_barrier
	s_branch .LBB0_184
.LBB0_182:
	s_or_b64 exec, exec, s[8:9]
	s_add_u32 s6, s6, s68
	s_addc_u32 s7, s7, s62
	s_add_u32 s6, s6, s68
	s_addc_u32 s7, s7, s62
	v_add_u32_e32 v2, 0x800, v2
	s_mov_b64 s[8:9], 0

; __device__ __forceinline__ void fill_rowscales(float* rsl, const float* ssq, float inv_n, const g8::Order& S) {
;   const int tid = opaque_tid();
;   g8::Unit u;
;   __syncthreads();
;   for (int i = 0; S.next(i, u); ++i) {
;     if (tid < 256) {
;       const float4* s4 = (const float4*)(ssq + (size_t)(u.pm * 256 + tid) * 16);
;       float s = 0.f;
;       for (int k = 0; k < 4; ++k) { float4 v = s4[k]; s += v.x + v.y + v.z + v.w; }
;       rsl[i * 256 + tid] = rsqrtf(s * inv_n + EPS);
;     }
;   }
;   __syncthreads();
; }
; __device__ __forceinline__ void phase_up(const Params& p, int l, char* lds) {
;     ...
;   fill_rowscales(rsl, (const float*)(WS(p) + O_SSQ), 1.f / DM, S);
.LBB0_2452:
	s_or_b64 exec, exec, s[0:1]
	s_waitcnt lgkmcnt(0)
	s_barrier
	s_mov_b32 s0, 0
	s_ashr_i32 s1, s0, 31
	s_add_u32 s0, s82, s0
	s_addc_u32 s1, s83, s1
	s_add_u32 s0, s0, 0x9a00000
	v_mov_b32_e32 v0, v145
	s_movk_i32 s2, 0x100
	s_addc_u32 s1, s1, 0
	s_mov_b64 s[8:9], s[70:71]
	s_mov_b64 s[6:7], -1
	v_lshl_add_u32 v2, v0, 2, v190
	v_readfirstlane_b32 s2, v0
	s_cmp_lt_u32 s2, 0x100
	s_cbranch_scc1 .Lfr_up_lo
	s_add_u32 s8, s8, s68
	s_addc_u32 s9, s9, s62
	v_and_b32_e32 v0, 0xff, v0

; __device__ __forceinline__ void fill_rowscales(float* rsl, const float* ssq, float inv_n, const g8::Order& S) {
;     ...
;   for (int i = 0; S.next(i, u); ++i) {
;     if (tid < 256) {
;       const float4* s4 = (const float4*)(ssq + (size_t)(u.pm * 256 + tid) * 16);
;       float s = 0.f;
;       for (int k = 0; k < 4; ++k) { float4 v = s4[k]; s += v.x + v.y + v.z + v.w; }
;       rsl[i * 256 + tid] = rsqrtf(s * inv_n + EPS);
;     }
;   }
.LBB0_2453:
	s_or_b64 exec, exec, s[10:11]
	s_add_u32 s8, s8, s68
	s_addc_u32 s9, s9, s62
	s_add_u32 s8, s8, s68
	s_addc_u32 s9, s9, s62
	v_add_u32_e32 v2, 0x800, v2
	s_mov_b64 s[10:11], 0
